# v20
# speedup vs baseline: 1.0044x; 1.0044x over previous
; #define G_EPI_LOOP                                      \
;   _Pragma("unroll") for (int ai = 0; ai < 2; ++ai)      \
;   _Pragma("unroll") for (int bj = 0; bj < 2; ++bj)      \
;   _Pragma("unroll") for (int m = 0; m < 4; ++m)         \
;   _Pragma("unroll") for (int n = 0; n < 2; ++n)
; DEVI void phase_outproj(const Params& p, char* lds) {
;     ...
;     int tidl_ = tid0_;
;     asm volatile("" : "+v"(tidl_));
;     const int lane = tidl_ & 63, wid = tidl_ >> 6, wr = wid >> 2, wc = wid & 3, fr = lane & 15, fq = lane >> 4;
;     G_EPI_LOOP {
;       size_t o = (size_t)mt * 256 + G_J;
;       int ncol = nt * 256 + G_I;
;       const float* xr = (o < 16384) ? p.xp + o * 1024 : p.xs + (o - 16384) * 1024;
;       f32x4 res = *(const f32x4*)(xr + ncol);
;       *(f32x4*)(p.out + o * 1024 + ncol) = res + acc[ai][bj][m][n];
;       if (n == 1) asm volatile("" ::: "memory");
;     }
; DEVI void phase_norm2(const Params& p) {
;     ...
;           float4 w = *(const float4*)(p.norm2_w + (j * 64 + lane) * 4);
;           uint2 ov;
;           ov.x = pk2(v[u][j].x * rs * w.x, v[u][j].y * rs * w.y);
;           ov.y = pk2(v[u][j].z * rs * w.z, v[u][j].w * rs * w.w);
;           *(uint2*)(P_U2 + (size_t)o * 1024 + (j * 64 + lane) * 4) = ov;
.LBB0_312:
	s_or_b64 exec, exec, s[28:29]
	v_mov_b32_e32 v130, v142
	s_waitcnt vmcnt(0)
	s_barrier
	v_readlane_b32 s72, v255, 3
	v_lshrrev_b32_e32 v131, 1, v130
	v_and_b32_e32 v128, 15, v130
	v_and_b32_e32 v131, 0x60, v131
	v_or3_b32 v128, v128, v131, s49
	v_ashrrev_i32_e32 v131, 2, v130
	v_and_b32_e32 v131, 0xffffffc0, v131
	v_lshrrev_b32_e32 v130, 2, v130
	v_lshl_add_u32 v131, s50, 8, v131
	v_lshlrev_b64 v[132:133], 12, v[128:129]
	v_readlane_b32 s74, v255, 5
	v_readlane_b32 s75, v255, 6
	v_and_or_b32 v130, v130, 12, v131
	v_readlane_b32 s73, v255, 4
	v_lshl_add_u64 v[134:135], s[74:75], 0, v[132:133]
	v_ashrrev_i32_e32 v131, 31, v130
	v_lshl_add_u64 v[134:135], v[134:135], 0, s[26:27]
	v_lshl_add_u64 v[136:137], s[72:73], 0, v[132:133]
	v_cndmask_b32_e64 v135, v135, v137, s[2:3]
	v_cndmask_b32_e64 v134, v134, v136, s[2:3]
	v_lshlrev_b64 v[140:141], 2, v[130:131]
	v_lshl_add_u64 v[130:131], v[134:135], 0, v[140:141]
	v_lshl_add_u64 v[132:133], s[62:63], 0, v[132:133]
	v_lshl_add_u64 v[132:133], v[132:133], 0, v[140:141]
	v_mov_b32_e32 v144, 0x10000
	v_mov_b32_e32 v145, 0
	v_mov_b32_e32 v146, 0x80000
	v_mov_b32_e32 v147, 0
	v_mov_b32_e32 v148, 0x90000
	v_mov_b32_e32 v149, 0
	v_lshl_add_u64 v[134:135], v[130:131], 0, v[144:145]
	v_lshl_add_u64 v[136:137], v[130:131], 0, v[146:147]
	v_lshl_add_u64 v[138:139], v[130:131], 0, v[148:149]
	v_lshl_add_u64 v[150:151], v[132:133], 0, v[144:145]
	v_lshl_add_u64 v[152:153], v[132:133], 0, v[146:147]
	v_lshl_add_u64 v[154:155], v[132:133], 0, v[148:149]
	v_lshl_add_u64 v[248:249], s[54:55], 0, v[140:141]
	v_lshlrev_b64 v[240:241], 11, v[128:129]
	v_mov_b32_e32 v250, 0x2764000
	v_mov_b32_e32 v251, 0
	v_lshl_add_u64 v[240:241], v[240:241], 0, v[250:251]
	v_lshl_add_u64 v[240:241], s[90:91], 0, v[240:241]
	v_lshrrev_b32_e32 v250, 1, v140
	v_lshl_add_u64 v[240:241], v[240:241], 0, v[250:251]
	v_mov_b32_e32 v250, 0x8000
	v_lshl_add_u64 v[242:243], v[240:241], 0, v[250:251]
	v_mov_b32_e32 v250, 0x40000
	v_lshl_add_u64 v[244:245], v[240:241], 0, v[250:251]
	v_mov_b32_e32 v250, 0x48000
	v_lshl_add_u64 v[246:247], v[240:241], 0, v[250:251]
	v_mov_b32_e32 v236, 0
	v_mov_b32_e32 v237, 0
	v_mov_b32_e32 v238, 0
	v_mov_b32_e32 v239, 0
	s_add_i32 s48, s48, s71
	s_add_i32 s47, s47, s71
	s_cmp_lt_u32 s48, s33
	v_readlane_b32 s76, v255, 7
	v_readlane_b32 s77, v255, 8
	v_readlane_b32 s78, v255, 9
	v_readlane_b32 s79, v255, 10
	v_readlane_b32 s80, v255, 11
	v_readlane_b32 s81, v255, 12
	v_readlane_b32 s82, v255, 13
	v_readlane_b32 s83, v255, 14
	v_readlane_b32 s84, v255, 15
	v_readlane_b32 s85, v255, 16
	v_readlane_b32 s86, v255, 17
	v_readlane_b32 s87, v255, 18
	global_load_dwordx4 v[204:207], v[248:249], off
	global_load_dwordx4 v[208:211], v[248:249], off offset:64
	global_load_dwordx4 v[212:215], v[248:249], off offset:128
	global_load_dwordx4 v[216:219], v[248:249], off offset:192
	global_load_dwordx4 v[220:223], v[248:249], off offset:512
	global_load_dwordx4 v[224:227], v[248:249], off offset:576
	global_load_dwordx4 v[228:231], v[248:249], off offset:640
	global_load_dwordx4 v[232:235], v[248:249], off offset:704
	global_load_dwordx4 v[156:159], v[130:131], off
	global_load_dwordx4 v[160:163], v[134:135], off
	global_load_dwordx4 v[168:171], v[130:131], off offset:64
	global_load_dwordx4 v[172:175], v[134:135], off offset:64
	global_load_dwordx4 v[176:179], v[130:131], off offset:128
	global_load_dwordx4 v[180:183], v[134:135], off offset:128
	global_load_dwordx4 v[184:187], v[130:131], off offset:192
	global_load_dwordx4 v[188:191], v[134:135], off offset:192
	global_load_dwordx4 v[192:195], v[136:137], off
	global_load_dwordx4 v[196:199], v[138:139], off
	global_load_dwordx4 v[200:203], v[136:137], off offset:64
	s_waitcnt vmcnt(10)
	v_pk_add_f32 v[124:125], v[124:125], v[156:157]
	v_pk_add_f32 v[126:127], v[126:127], v[158:159]
	global_store_dwordx4 v[132:133], v[124:127], off
	v_pk_mul_f32 v[248:249], v[124:125], v[204:205]
	v_pk_mul_f32 v[250:251], v[126:127], v[206:207]
	v_fmac_f32_e32 v236, v124, v124
	v_fmac_f32_e32 v236, v125, v125
	v_cvt_pk_bf16_f32 v248, v248, v249
	v_cvt_pk_bf16_f32 v249, v250, v251
	v_fmac_f32_e32 v236, v126, v126
	v_fmac_f32_e32 v236, v127, v127
	global_store_dwordx2 v[240:241], v[248:249], off
	global_load_dwordx4 v[156:159], v[138:139], off offset:64
	s_waitcnt vmcnt(12)
	v_pk_add_f32 v[120:121], v[120:121], v[160:161]
	v_pk_add_f32 v[122:123], v[122:123], v[162:163]
	global_store_dwordx4 v[150:151], v[120:123], off
	v_pk_mul_f32 v[248:249], v[120:121], v[204:205]
	v_pk_mul_f32 v[250:251], v[122:123], v[206:207]
	v_fmac_f32_e32 v237, v120, v120
	v_fmac_f32_e32 v237, v121, v121
	v_cvt_pk_bf16_f32 v248, v248, v249
	v_cvt_pk_bf16_f32 v249, v250, v251
	v_fmac_f32_e32 v237, v122, v122
	v_fmac_f32_e32 v237, v123, v123
	global_store_dwordx2 v[242:243], v[248:249], off
	global_load_dwordx4 v[160:163], v[136:137], off offset:128
	s_waitcnt vmcnt(14)
	v_pk_add_f32 v[116:117], v[116:117], v[168:169]
	v_pk_add_f32 v[118:119], v[118:119], v[170:171]
	global_store_dwordx4 v[132:133], v[116:119], off offset:64
	v_pk_mul_f32 v[248:249], v[116:117], v[208:209]
	v_pk_mul_f32 v[250:251], v[118:119], v[210:211]
	v_fmac_f32_e32 v236, v116, v116
	v_fmac_f32_e32 v236, v117, v117
	v_cvt_pk_bf16_f32 v248, v248, v249
	v_cvt_pk_bf16_f32 v249, v250, v251
	v_fmac_f32_e32 v236, v118, v118
	v_fmac_f32_e32 v236, v119, v119
	global_store_dwordx2 v[240:241], v[248:249], off offset:32
	global_load_dwordx4 v[168:171], v[138:139], off offset:128
	s_waitcnt vmcnt(16)
; #define G_EPI_LOOP                                      \
;   _Pragma("unroll") for (int ai = 0; ai < 2; ++ai)      \
;   _Pragma("unroll") for (int bj = 0; bj < 2; ++bj)      \
;   _Pragma("unroll") for (int m = 0; m < 4; ++m)         \
;   _Pragma("unroll") for (int n = 0; n < 2; ++n)
; DEVI void phase_outproj(const Params& p, char* lds) {
;     ...
;     G_EPI_LOOP {
;       size_t o = (size_t)mt * 256 + G_J;
;       int ncol = nt * 256 + G_I;
;       const float* xr = (o < 16384) ? p.xp + o * 1024 : p.xs + (o - 16384) * 1024;
;       f32x4 res = *(const f32x4*)(xr + ncol);
;       *(f32x4*)(p.out + o * 1024 + ncol) = res + acc[ai][bj][m][n];
;       if (n == 1) asm volatile("" ::: "memory");
;     }
; DEVI void phase_norm2(const Params& p) {
;     ...
;           float4 w = *(const float4*)(p.norm2_w + (j * 64 + lane) * 4);
;           uint2 ov;
;           ov.x = pk2(v[u][j].x * rs * w.x, v[u][j].y * rs * w.y);
;           ov.y = pk2(v[u][j].z * rs * w.z, v[u][j].w * rs * w.w);
;           *(uint2*)(P_U2 + (size_t)o * 1024 + (j * 64 + lane) * 4) = ov;
	v_pk_add_f32 v[112:113], v[112:113], v[172:173]
	v_pk_add_f32 v[114:115], v[114:115], v[174:175]
	global_store_dwordx4 v[150:151], v[112:115], off offset:64
	v_pk_mul_f32 v[248:249], v[112:113], v[208:209]
	v_pk_mul_f32 v[250:251], v[114:115], v[210:211]
	v_fmac_f32_e32 v237, v112, v112
	v_fmac_f32_e32 v237, v113, v113
	v_cvt_pk_bf16_f32 v248, v248, v249
	v_cvt_pk_bf16_f32 v249, v250, v251
	v_fmac_f32_e32 v237, v114, v114
	v_fmac_f32_e32 v237, v115, v115
	global_store_dwordx2 v[242:243], v[248:249], off offset:32
	global_load_dwordx4 v[172:175], v[136:137], off offset:192
	s_waitcnt vmcnt(18)
	v_pk_add_f32 v[108:109], v[108:109], v[176:177]
	v_pk_add_f32 v[110:111], v[110:111], v[178:179]
	global_store_dwordx4 v[132:133], v[108:111], off offset:128
	v_pk_mul_f32 v[248:249], v[108:109], v[212:213]
	v_pk_mul_f32 v[250:251], v[110:111], v[214:215]
	v_fmac_f32_e32 v236, v108, v108
	v_fmac_f32_e32 v236, v109, v109
	v_cvt_pk_bf16_f32 v248, v248, v249
	v_cvt_pk_bf16_f32 v249, v250, v251
	v_fmac_f32_e32 v236, v110, v110
	v_fmac_f32_e32 v236, v111, v111
	global_store_dwordx2 v[240:241], v[248:249], off offset:64
	global_load_dwordx4 v[176:179], v[138:139], off offset:192
	s_waitcnt vmcnt(20)
	v_pk_add_f32 v[104:105], v[104:105], v[180:181]
	v_pk_add_f32 v[106:107], v[106:107], v[182:183]
	global_store_dwordx4 v[150:151], v[104:107], off offset:128
	v_pk_mul_f32 v[248:249], v[104:105], v[212:213]
	v_pk_mul_f32 v[250:251], v[106:107], v[214:215]
	v_fmac_f32_e32 v237, v104, v104
	v_fmac_f32_e32 v237, v105, v105
	v_cvt_pk_bf16_f32 v248, v248, v249
	v_cvt_pk_bf16_f32 v249, v250, v251
	v_fmac_f32_e32 v237, v106, v106
	v_fmac_f32_e32 v237, v107, v107
	global_store_dwordx2 v[242:243], v[248:249], off offset:64
	global_load_dwordx4 v[180:183], v[130:131], off offset:512
	s_waitcnt vmcnt(22)
	v_pk_add_f32 v[100:101], v[100:101], v[184:185]
	v_pk_add_f32 v[102:103], v[102:103], v[186:187]
	global_store_dwordx4 v[132:133], v[100:103], off offset:192
	v_pk_mul_f32 v[248:249], v[100:101], v[216:217]
	v_pk_mul_f32 v[250:251], v[102:103], v[218:219]
	v_fmac_f32_e32 v236, v100, v100
	v_fmac_f32_e32 v236, v101, v101
	v_cvt_pk_bf16_f32 v248, v248, v249
	v_cvt_pk_bf16_f32 v249, v250, v251
	v_fmac_f32_e32 v236, v102, v102
	v_fmac_f32_e32 v236, v103, v103
	global_store_dwordx2 v[240:241], v[248:249], off offset:96
	global_load_dwordx4 v[184:187], v[134:135], off offset:512
	s_waitcnt vmcnt(24)
	v_pk_add_f32 v[96:97], v[96:97], v[188:189]
	v_pk_add_f32 v[98:99], v[98:99], v[190:191]
	global_store_dwordx4 v[150:151], v[96:99], off offset:192
	v_pk_mul_f32 v[248:249], v[96:97], v[216:217]
	v_pk_mul_f32 v[250:251], v[98:99], v[218:219]
	v_fmac_f32_e32 v237, v96, v96
	v_fmac_f32_e32 v237, v97, v97
	v_cvt_pk_bf16_f32 v248, v248, v249
	v_cvt_pk_bf16_f32 v249, v250, v251
	v_fmac_f32_e32 v237, v98, v98
	v_fmac_f32_e32 v237, v99, v99
	global_store_dwordx2 v[242:243], v[248:249], off offset:96
	global_load_dwordx4 v[188:191], v[130:131], off offset:576
	s_waitcnt vmcnt(26)
	v_pk_add_f32 v[92:93], v[92:93], v[192:193]
	v_pk_add_f32 v[94:95], v[94:95], v[194:195]
	global_store_dwordx4 v[152:153], v[92:95], off
	v_pk_mul_f32 v[248:249], v[92:93], v[204:205]
	v_pk_mul_f32 v[250:251], v[94:95], v[206:207]
	v_fmac_f32_e32 v238, v92, v92
	v_fmac_f32_e32 v238, v93, v93
	v_cvt_pk_bf16_f32 v248, v248, v249
	v_cvt_pk_bf16_f32 v249, v250, v251
	v_fmac_f32_e32 v238, v94, v94
	v_fmac_f32_e32 v238, v95, v95
	global_store_dwordx2 v[244:245], v[248:249], off
	global_load_dwordx4 v[192:195], v[134:135], off offset:576
	s_waitcnt vmcnt(28)
	v_pk_add_f32 v[88:89], v[88:89], v[196:197]
	v_pk_add_f32 v[90:91], v[90:91], v[198:199]
	global_store_dwordx4 v[154:155], v[88:91], off
	v_pk_mul_f32 v[248:249], v[88:89], v[204:205]
	v_pk_mul_f32 v[250:251], v[90:91], v[206:207]
	v_fmac_f32_e32 v239, v88, v88
	v_fmac_f32_e32 v239, v89, v89
	v_cvt_pk_bf16_f32 v248, v248, v249
	v_cvt_pk_bf16_f32 v249, v250, v251
	v_fmac_f32_e32 v239, v90, v90
	v_fmac_f32_e32 v239, v91, v91
	global_store_dwordx2 v[246:247], v[248:249], off
	global_load_dwordx4 v[196:199], v[130:131], off offset:640
	s_waitcnt vmcnt(30)
	v_pk_add_f32 v[84:85], v[84:85], v[200:201]
	v_pk_add_f32 v[86:87], v[86:87], v[202:203]
	global_store_dwordx4 v[152:153], v[84:87], off offset:64
	v_pk_mul_f32 v[248:249], v[84:85], v[208:209]
	v_pk_mul_f32 v[250:251], v[86:87], v[210:211]
	v_fmac_f32_e32 v238, v84, v84
	v_fmac_f32_e32 v238, v85, v85
	v_cvt_pk_bf16_f32 v248, v248, v249
	v_cvt_pk_bf16_f32 v249, v250, v251
	v_fmac_f32_e32 v238, v86, v86
	v_fmac_f32_e32 v238, v87, v87
	global_store_dwordx2 v[244:245], v[248:249], off offset:32
	global_load_dwordx4 v[200:203], v[134:135], off offset:640
	s_waitcnt vmcnt(30)
	v_pk_add_f32 v[80:81], v[80:81], v[156:157]
	v_pk_add_f32 v[82:83], v[82:83], v[158:159]
	global_store_dwordx4 v[154:155], v[80:83], off offset:64
	v_pk_mul_f32 v[248:249], v[80:81], v[208:209]
	v_pk_mul_f32 v[250:251], v[82:83], v[210:211]
	v_fmac_f32_e32 v239, v80, v80
	v_fmac_f32_e32 v239, v81, v81
	v_cvt_pk_bf16_f32 v248, v248, v249
	v_cvt_pk_bf16_f32 v249, v250, v251
	v_fmac_f32_e32 v239, v82, v82
	v_fmac_f32_e32 v239, v83, v83
	global_store_dwordx2 v[246:247], v[248:249], off offset:32
	global_load_dwordx4 v[156:159], v[130:131], off offset:704
	s_waitcnt vmcnt(30)
	v_pk_add_f32 v[76:77], v[76:77], v[160:161]
	v_pk_add_f32 v[78:79], v[78:79], v[162:163]
	global_store_dwordx4 v[152:153], v[76:79], off offset:128
	v_pk_mul_f32 v[248:249], v[76:77], v[212:213]
	v_pk_mul_f32 v[250:251], v[78:79], v[214:215]
	v_fmac_f32_e32 v238, v76, v76
	v_fmac_f32_e32 v238, v77, v77
	v_cvt_pk_bf16_f32 v248, v248, v249
	v_cvt_pk_bf16_f32 v249, v250, v251
	v_fmac_f32_e32 v238, v78, v78
	v_fmac_f32_e32 v238, v79, v79
	global_store_dwordx2 v[244:245], v[248:249], off offset:64
	global_load_dwordx4 v[160:163], v[134:135], off offset:704
	s_waitcnt vmcnt(30)
; #define G_EPI_LOOP                                      \
;   _Pragma("unroll") for (int ai = 0; ai < 2; ++ai)      \
;   _Pragma("unroll") for (int bj = 0; bj < 2; ++bj)      \
;   _Pragma("unroll") for (int m = 0; m < 4; ++m)         \
;   _Pragma("unroll") for (int n = 0; n < 2; ++n)
; DEVI void phase_outproj(const Params& p, char* lds) {
;     ...
;     G_EPI_LOOP {
;       size_t o = (size_t)mt * 256 + G_J;
;       int ncol = nt * 256 + G_I;
;       const float* xr = (o < 16384) ? p.xp + o * 1024 : p.xs + (o - 16384) * 1024;
;       f32x4 res = *(const f32x4*)(xr + ncol);
;       *(f32x4*)(p.out + o * 1024 + ncol) = res + acc[ai][bj][m][n];
;       if (n == 1) asm volatile("" ::: "memory");
;     }
; DEVI void phase_norm2(const Params& p) {
;     ...
;           float4 w = *(const float4*)(p.norm2_w + (j * 64 + lane) * 4);
;           uint2 ov;
;           ov.x = pk2(v[u][j].x * rs * w.x, v[u][j].y * rs * w.y);
;           ov.y = pk2(v[u][j].z * rs * w.z, v[u][j].w * rs * w.w);
;           *(uint2*)(P_U2 + (size_t)o * 1024 + (j * 64 + lane) * 4) = ov;
	v_pk_add_f32 v[72:73], v[72:73], v[168:169]
	v_pk_add_f32 v[74:75], v[74:75], v[170:171]
	global_store_dwordx4 v[154:155], v[72:75], off offset:128
	v_pk_mul_f32 v[248:249], v[72:73], v[212:213]
	v_pk_mul_f32 v[250:251], v[74:75], v[214:215]
	v_fmac_f32_e32 v239, v72, v72
	v_fmac_f32_e32 v239, v73, v73
	v_cvt_pk_bf16_f32 v248, v248, v249
	v_cvt_pk_bf16_f32 v249, v250, v251
	v_fmac_f32_e32 v239, v74, v74
	v_fmac_f32_e32 v239, v75, v75
	global_store_dwordx2 v[246:247], v[248:249], off offset:64
	global_load_dwordx4 v[168:171], v[136:137], off offset:512
	s_waitcnt vmcnt(30)
	v_pk_add_f32 v[68:69], v[68:69], v[172:173]
	v_pk_add_f32 v[70:71], v[70:71], v[174:175]
	global_store_dwordx4 v[152:153], v[68:71], off offset:192
	v_pk_mul_f32 v[248:249], v[68:69], v[216:217]
	v_pk_mul_f32 v[250:251], v[70:71], v[218:219]
	v_fmac_f32_e32 v238, v68, v68
	v_fmac_f32_e32 v238, v69, v69
	v_cvt_pk_bf16_f32 v248, v248, v249
	v_cvt_pk_bf16_f32 v249, v250, v251
	v_fmac_f32_e32 v238, v70, v70
	v_fmac_f32_e32 v238, v71, v71
	global_store_dwordx2 v[244:245], v[248:249], off offset:96
	global_load_dwordx4 v[172:175], v[138:139], off offset:512
	s_waitcnt vmcnt(30)
	v_pk_add_f32 v[60:61], v[60:61], v[176:177]
	v_pk_add_f32 v[62:63], v[62:63], v[178:179]
	global_store_dwordx4 v[154:155], v[60:63], off offset:192
	v_pk_mul_f32 v[248:249], v[60:61], v[216:217]
	v_pk_mul_f32 v[250:251], v[62:63], v[218:219]
	v_fmac_f32_e32 v239, v60, v60
	v_fmac_f32_e32 v239, v61, v61
	v_cvt_pk_bf16_f32 v248, v248, v249
	v_cvt_pk_bf16_f32 v249, v250, v251
	v_fmac_f32_e32 v239, v62, v62
	v_fmac_f32_e32 v239, v63, v63
	global_store_dwordx2 v[246:247], v[248:249], off offset:96
	global_load_dwordx4 v[176:179], v[136:137], off offset:576
	s_waitcnt vmcnt(30)
	v_pk_add_f32 v[64:65], v[64:65], v[180:181]
	v_pk_add_f32 v[66:67], v[66:67], v[182:183]
	global_store_dwordx4 v[132:133], v[64:67], off offset:512
	v_pk_mul_f32 v[248:249], v[64:65], v[220:221]
	v_pk_mul_f32 v[250:251], v[66:67], v[222:223]
	v_fmac_f32_e32 v236, v64, v64
	v_fmac_f32_e32 v236, v65, v65
	v_cvt_pk_bf16_f32 v248, v248, v249
	v_cvt_pk_bf16_f32 v249, v250, v251
	v_fmac_f32_e32 v236, v66, v66
	v_fmac_f32_e32 v236, v67, v67
	global_store_dwordx2 v[240:241], v[248:249], off offset:256
	global_load_dwordx4 v[180:183], v[138:139], off offset:576
	s_waitcnt vmcnt(30)
	v_pk_add_f32 v[56:57], v[56:57], v[184:185]
	v_pk_add_f32 v[58:59], v[58:59], v[186:187]
	global_store_dwordx4 v[150:151], v[56:59], off offset:512
	v_pk_mul_f32 v[248:249], v[56:57], v[220:221]
	v_pk_mul_f32 v[250:251], v[58:59], v[222:223]
	v_fmac_f32_e32 v237, v56, v56
	v_fmac_f32_e32 v237, v57, v57
	v_cvt_pk_bf16_f32 v248, v248, v249
	v_cvt_pk_bf16_f32 v249, v250, v251
	v_fmac_f32_e32 v237, v58, v58
	v_fmac_f32_e32 v237, v59, v59
	global_store_dwordx2 v[242:243], v[248:249], off offset:256
	global_load_dwordx4 v[184:187], v[136:137], off offset:640
	s_waitcnt vmcnt(30)
	v_pk_add_f32 v[52:53], v[52:53], v[188:189]
	v_pk_add_f32 v[54:55], v[54:55], v[190:191]
	global_store_dwordx4 v[132:133], v[52:55], off offset:576
	v_pk_mul_f32 v[248:249], v[52:53], v[224:225]
	v_pk_mul_f32 v[250:251], v[54:55], v[226:227]
	v_fmac_f32_e32 v236, v52, v52
	v_fmac_f32_e32 v236, v53, v53
	v_cvt_pk_bf16_f32 v248, v248, v249
	v_cvt_pk_bf16_f32 v249, v250, v251
	v_fmac_f32_e32 v236, v54, v54
	v_fmac_f32_e32 v236, v55, v55
	global_store_dwordx2 v[240:241], v[248:249], off offset:288
	global_load_dwordx4 v[188:191], v[138:139], off offset:640
	s_waitcnt vmcnt(30)
	v_pk_add_f32 v[48:49], v[48:49], v[192:193]
	v_pk_add_f32 v[50:51], v[50:51], v[194:195]
	global_store_dwordx4 v[150:151], v[48:51], off offset:576
	v_pk_mul_f32 v[248:249], v[48:49], v[224:225]
	v_pk_mul_f32 v[250:251], v[50:51], v[226:227]
	v_fmac_f32_e32 v237, v48, v48
	v_fmac_f32_e32 v237, v49, v49
	v_cvt_pk_bf16_f32 v248, v248, v249
	v_cvt_pk_bf16_f32 v249, v250, v251
	v_fmac_f32_e32 v237, v50, v50
	v_fmac_f32_e32 v237, v51, v51
	global_store_dwordx2 v[242:243], v[248:249], off offset:288
	global_load_dwordx4 v[192:195], v[136:137], off offset:704
	s_waitcnt vmcnt(30)
	v_pk_add_f32 v[44:45], v[44:45], v[196:197]
	v_pk_add_f32 v[46:47], v[46:47], v[198:199]
	global_store_dwordx4 v[132:133], v[44:47], off offset:640
	v_pk_mul_f32 v[248:249], v[44:45], v[228:229]
	v_pk_mul_f32 v[250:251], v[46:47], v[230:231]
	v_fmac_f32_e32 v236, v44, v44
	v_fmac_f32_e32 v236, v45, v45
	v_cvt_pk_bf16_f32 v248, v248, v249
	v_cvt_pk_bf16_f32 v249, v250, v251
	v_fmac_f32_e32 v236, v46, v46
	v_fmac_f32_e32 v236, v47, v47
	global_store_dwordx2 v[240:241], v[248:249], off offset:320
	global_load_dwordx4 v[196:199], v[138:139], off offset:704
	s_waitcnt vmcnt(30)
	v_pk_add_f32 v[40:41], v[40:41], v[200:201]
	v_pk_add_f32 v[42:43], v[42:43], v[202:203]
	global_store_dwordx4 v[150:151], v[40:43], off offset:640
	v_pk_mul_f32 v[248:249], v[40:41], v[228:229]
	v_pk_mul_f32 v[250:251], v[42:43], v[230:231]
	v_fmac_f32_e32 v237, v40, v40
	v_fmac_f32_e32 v237, v41, v41
	v_cvt_pk_bf16_f32 v248, v248, v249
	v_cvt_pk_bf16_f32 v249, v250, v251
	v_fmac_f32_e32 v237, v42, v42
	v_fmac_f32_e32 v237, v43, v43
	global_store_dwordx2 v[242:243], v[248:249], off offset:320
	s_waitcnt vmcnt(29)
	v_pk_add_f32 v[36:37], v[36:37], v[156:157]
	v_pk_add_f32 v[38:39], v[38:39], v[158:159]
	global_store_dwordx4 v[132:133], v[36:39], off offset:704
	v_pk_mul_f32 v[248:249], v[36:37], v[232:233]
	v_pk_mul_f32 v[250:251], v[38:39], v[234:235]
	v_fmac_f32_e32 v236, v36, v36
	v_fmac_f32_e32 v236, v37, v37
	v_cvt_pk_bf16_f32 v248, v248, v249
	v_cvt_pk_bf16_f32 v249, v250, v251
	v_fmac_f32_e32 v236, v38, v38
	v_fmac_f32_e32 v236, v39, v39
	global_store_dwordx2 v[240:241], v[248:249], off offset:352
	s_waitcnt vmcnt(28)
; #define G_EPI_LOOP                                      \
;   _Pragma("unroll") for (int ai = 0; ai < 2; ++ai)      \
;   _Pragma("unroll") for (int bj = 0; bj < 2; ++bj)      \
;   _Pragma("unroll") for (int m = 0; m < 4; ++m)         \
;   _Pragma("unroll") for (int n = 0; n < 2; ++n)
; DEVI void phase_outproj(const Params& p, char* lds) {
;     ...
;     G_EPI_LOOP {
;       size_t o = (size_t)mt * 256 + G_J;
;       int ncol = nt * 256 + G_I;
;       const float* xr = (o < 16384) ? p.xp + o * 1024 : p.xs + (o - 16384) * 1024;
;       f32x4 res = *(const f32x4*)(xr + ncol);
;       *(f32x4*)(p.out + o * 1024 + ncol) = res + acc[ai][bj][m][n];
;       if (n == 1) asm volatile("" ::: "memory");
;     }
; DEVI void phase_norm2(const Params& p) {
;     ...
;       float ss = 0.f;
; #pragma unroll
;       for (int j = 0; j < 4; ++j) ss += v[u][j].x * v[u][j].x + v[u][j].y * v[u][j].y + v[u][j].z * v[u][j].z + v[u][j].w * v[u][j].w;
;       ss = wsum(ss);
;       float rs = rsqrtf(ss * (1.f / 1024.f) + EPSN);
	v_pk_add_f32 v[32:33], v[32:33], v[160:161]
	v_pk_add_f32 v[34:35], v[34:35], v[162:163]
	global_store_dwordx4 v[150:151], v[32:35], off offset:704
	v_pk_mul_f32 v[248:249], v[32:33], v[232:233]
	v_pk_mul_f32 v[250:251], v[34:35], v[234:235]
	v_fmac_f32_e32 v237, v32, v32
	v_fmac_f32_e32 v237, v33, v33
	v_cvt_pk_bf16_f32 v248, v248, v249
	v_cvt_pk_bf16_f32 v249, v250, v251
	v_fmac_f32_e32 v237, v34, v34
	v_fmac_f32_e32 v237, v35, v35
	global_store_dwordx2 v[242:243], v[248:249], off offset:352
	s_waitcnt vmcnt(27)
	v_pk_add_f32 v[28:29], v[28:29], v[168:169]
	v_pk_add_f32 v[30:31], v[30:31], v[170:171]
	global_store_dwordx4 v[152:153], v[28:31], off offset:512
	v_pk_mul_f32 v[248:249], v[28:29], v[220:221]
	v_pk_mul_f32 v[250:251], v[30:31], v[222:223]
	v_fmac_f32_e32 v238, v28, v28
	v_fmac_f32_e32 v238, v29, v29
	v_cvt_pk_bf16_f32 v248, v248, v249
	v_cvt_pk_bf16_f32 v249, v250, v251
	v_fmac_f32_e32 v238, v30, v30
	v_fmac_f32_e32 v238, v31, v31
	global_store_dwordx2 v[244:245], v[248:249], off offset:256
	s_waitcnt vmcnt(26)
	v_pk_add_f32 v[24:25], v[24:25], v[172:173]
	v_pk_add_f32 v[26:27], v[26:27], v[174:175]
	global_store_dwordx4 v[154:155], v[24:27], off offset:512
	v_pk_mul_f32 v[248:249], v[24:25], v[220:221]
	v_pk_mul_f32 v[250:251], v[26:27], v[222:223]
	v_fmac_f32_e32 v239, v24, v24
	v_fmac_f32_e32 v239, v25, v25
	v_cvt_pk_bf16_f32 v248, v248, v249
	v_cvt_pk_bf16_f32 v249, v250, v251
	v_fmac_f32_e32 v239, v26, v26
	v_fmac_f32_e32 v239, v27, v27
	global_store_dwordx2 v[246:247], v[248:249], off offset:256
	s_waitcnt vmcnt(25)
	v_pk_add_f32 v[20:21], v[20:21], v[176:177]
	v_pk_add_f32 v[22:23], v[22:23], v[178:179]
	global_store_dwordx4 v[152:153], v[20:23], off offset:576
	v_pk_mul_f32 v[248:249], v[20:21], v[224:225]
	v_pk_mul_f32 v[250:251], v[22:23], v[226:227]
	v_fmac_f32_e32 v238, v20, v20
	v_fmac_f32_e32 v238, v21, v21
	v_cvt_pk_bf16_f32 v248, v248, v249
	v_cvt_pk_bf16_f32 v249, v250, v251
	v_fmac_f32_e32 v238, v22, v22
	v_fmac_f32_e32 v238, v23, v23
	global_store_dwordx2 v[244:245], v[248:249], off offset:288
	s_waitcnt vmcnt(24)
	v_pk_add_f32 v[16:17], v[16:17], v[180:181]
	v_pk_add_f32 v[18:19], v[18:19], v[182:183]
	global_store_dwordx4 v[154:155], v[16:19], off offset:576
	v_pk_mul_f32 v[248:249], v[16:17], v[224:225]
	v_pk_mul_f32 v[250:251], v[18:19], v[226:227]
	v_fmac_f32_e32 v239, v16, v16
	v_fmac_f32_e32 v239, v17, v17
	v_cvt_pk_bf16_f32 v248, v248, v249
	v_cvt_pk_bf16_f32 v249, v250, v251
	v_fmac_f32_e32 v239, v18, v18
	v_fmac_f32_e32 v239, v19, v19
	global_store_dwordx2 v[246:247], v[248:249], off offset:288
	s_waitcnt vmcnt(23)
	v_pk_add_f32 v[12:13], v[12:13], v[184:185]
	v_pk_add_f32 v[14:15], v[14:15], v[186:187]
	global_store_dwordx4 v[152:153], v[12:15], off offset:640
	v_pk_mul_f32 v[248:249], v[12:13], v[228:229]
	v_pk_mul_f32 v[250:251], v[14:15], v[230:231]
	v_fmac_f32_e32 v238, v12, v12
	v_fmac_f32_e32 v238, v13, v13
	v_cvt_pk_bf16_f32 v248, v248, v249
	v_cvt_pk_bf16_f32 v249, v250, v251
	v_fmac_f32_e32 v238, v14, v14
	v_fmac_f32_e32 v238, v15, v15
	global_store_dwordx2 v[244:245], v[248:249], off offset:320
	s_waitcnt vmcnt(22)
	v_pk_add_f32 v[8:9], v[8:9], v[188:189]
	v_pk_add_f32 v[10:11], v[10:11], v[190:191]
	global_store_dwordx4 v[154:155], v[8:11], off offset:640
	v_pk_mul_f32 v[248:249], v[8:9], v[228:229]
	v_pk_mul_f32 v[250:251], v[10:11], v[230:231]
	v_fmac_f32_e32 v239, v8, v8
	v_fmac_f32_e32 v239, v9, v9
	v_cvt_pk_bf16_f32 v248, v248, v249
	v_cvt_pk_bf16_f32 v249, v250, v251
	v_fmac_f32_e32 v239, v10, v10
	v_fmac_f32_e32 v239, v11, v11
	global_store_dwordx2 v[246:247], v[248:249], off offset:320
	s_waitcnt vmcnt(21)
	v_pk_add_f32 v[4:5], v[4:5], v[192:193]
	v_pk_add_f32 v[6:7], v[6:7], v[194:195]
	global_store_dwordx4 v[152:153], v[4:7], off offset:704
	v_pk_mul_f32 v[248:249], v[4:5], v[232:233]
	v_pk_mul_f32 v[250:251], v[6:7], v[234:235]
	v_fmac_f32_e32 v238, v4, v4
	v_fmac_f32_e32 v238, v5, v5
	v_cvt_pk_bf16_f32 v248, v248, v249
	v_cvt_pk_bf16_f32 v249, v250, v251
	v_fmac_f32_e32 v238, v6, v6
	v_fmac_f32_e32 v238, v7, v7
	global_store_dwordx2 v[244:245], v[248:249], off offset:352
	s_waitcnt vmcnt(20)
	v_pk_add_f32 v[0:1], v[0:1], v[196:197]
	v_pk_add_f32 v[2:3], v[2:3], v[198:199]
	global_store_dwordx4 v[154:155], v[0:3], off offset:704
	v_pk_mul_f32 v[248:249], v[0:1], v[232:233]
	v_pk_mul_f32 v[250:251], v[2:3], v[234:235]
	v_fmac_f32_e32 v239, v0, v0
	v_fmac_f32_e32 v239, v1, v1
	v_cvt_pk_bf16_f32 v248, v248, v249
	v_cvt_pk_bf16_f32 v249, v250, v251
	v_fmac_f32_e32 v239, v2, v2
	v_fmac_f32_e32 v239, v3, v3
	global_store_dwordx2 v[246:247], v[248:249], off offset:352
	v_mbcnt_lo_u32_b32 v250, -1, 0
	v_mbcnt_hi_u32_b32 v250, -1, v250
	v_xor_b32_e32 v251, 16, v250
	v_xor_b32_e32 v252, 32, v250
	v_lshlrev_b32_e32 v251, 2, v251
	v_lshlrev_b32_e32 v252, 2, v252
	ds_bpermute_b32 v248, v251, v236
	s_waitcnt lgkmcnt(0)
	v_add_f32_e32 v236, v236, v248
	ds_bpermute_b32 v248, v251, v237
	s_waitcnt lgkmcnt(0)
	v_add_f32_e32 v237, v237, v248
	ds_bpermute_b32 v248, v251, v238
	s_waitcnt lgkmcnt(0)
	v_add_f32_e32 v238, v238, v248
	ds_bpermute_b32 v248, v251, v239
	s_waitcnt lgkmcnt(0)
	v_add_f32_e32 v239, v239, v248
	ds_bpermute_b32 v248, v252, v236
	s_waitcnt lgkmcnt(0)
	v_add_f32_e32 v236, v236, v248
	ds_bpermute_b32 v248, v252, v237
	s_waitcnt lgkmcnt(0)
	v_add_f32_e32 v237, v237, v248
	ds_bpermute_b32 v248, v252, v238
	s_waitcnt lgkmcnt(0)
	v_add_f32_e32 v238, v238, v248
	ds_bpermute_b32 v248, v252, v239
	s_waitcnt lgkmcnt(0)
	v_add_f32_e32 v239, v239, v248
	v_lshrrev_b32_e32 v253, 8, v142
	v_lshl_add_u32 v253, s50, 1, v253
	v_lshlrev_b32_e32 v253, 2, v253
	v_lshl_add_u32 v249, v128, 5, v253
	v_add_u32_e32 v249, 0xc764000, v249
	v_add_u32_e32 v250, 0x1000, v249
	global_store_dword v249, v236, s[90:91]
	global_store_dword v249, v237, s[90:91] offset:512
	global_store_dword v250, v238, s[90:91]
	global_store_dword v250, v239, s[90:91] offset:512
	s_cmp_lt_u32 s48, s33
	s_cbranch_scc0 .LBB0_323

; DEVI void phase_norm2(const Params& p) {
;     ...
;   }
; }
; DEVI void phase_up(const Params& p, char* lds) {
;   int tid0_ = threadIdx.x;
;   asm volatile("" : "+v"(tid0_));
;   for (TileIter it = tile_iter(320 * 16); it.j < it.end; it.j += it.step) {
;     int mt, nt;
;     tile_decode(it.j, 320, 16, 4, mt, nt);
;     f32x4 acc[2][2][4][2];
;     gemm_core(P_WT_UP + (size_t)nt * 256 * 1024, 1024, P_U2 + (size_t)mt * 256 * 1024, 1024, 16, lds, acc);
.LBB0_333:
	s_or_b64 exec, exec, s[2:3]
	s_lshl_b32 s38, s64, 3
	s_mul_i32 s39, s64, 24
	s_branch .Lup_entry
.Lup_entry:
	s_mul_i32 s2, s51, 0x1400
	s_mul_i32 s1, s51, 0x280
	s_addk_i32 s2, 0x1400
	s_add_i32 s1, s1, s70
	s_lshr_b32 s36, s2, 3
	v_mov_b32_e32 v140, v164
	s_cmp_ge_u32 s1, s36
	s_barrier
	s_cbranch_scc1 .LBB0_369
	s_add_u32 s37, s90, 0xf80000
	s_addc_u32 s40, s91, 0
	s_movk_i32 s41, 0x2000
	v_mov_b32_e32 v129, 0
	s_mov_b32 s42, 0x10000
	s_mov_b32 s43, 0x14000
	s_mov_b64 s[2:3], 0x80
	s_mov_b32 s44, 0x18000
	s_mov_b32 s45, 0x1c000
	s_mov_b64 s[4:5], 0xfc0080
	s_mov_b64 s[6:7], 0x2764100
	s_mov_b64 s[10:11], 0xf80100
	s_mov_b64 s[12:13], 0x27a4100
	s_mov_b64 s[14:15], 0xfc0100
	s_mov_b64 s[16:17], 0x2764180
	s_mov_b64 s[18:19], 0xf80180
	s_mov_b64 s[20:21], 0x27a4180
	s_movk_i32 s46, 0x100
	s_movk_i32 s47, 0x60
	s_mov_b32 s48, 0x7fffffc0
	s_movk_i32 s49, 0x210
	s_movk_i32 s50, 0x600
	s_movk_i32 s51, 0x5ff
	s_movk_i32 s52, 0x17ff
	v_mov_b32_e32 v141, 1
	v_mov_b32_e32 v142, 0x10800
	v_mov_b32_e32 v143, 0x12900
	s_waitcnt vmcnt(0)
	s_branch .LBB0_355

; #define G_EPI_LOOP                                      \
;   _Pragma("unroll") for (int ai = 0; ai < 2; ++ai)      \
;   _Pragma("unroll") for (int bj = 0; bj < 2; ++bj)      \
;   _Pragma("unroll") for (int m = 0; m < 4; ++m)         \
;   _Pragma("unroll") for (int n = 0; n < 2; ++n)
; DEVI void phase_norm2(const Params& p) {
;     ...
;       ss = wsum(ss);
;       float rs = rsqrtf(ss * (1.f / 1024.f) + EPSN);
; DEVI void phase_down(const Params& p, char* lds) {
;     ...
;     int tidl_ = tid0_;
;     asm volatile("" : "+v"(tidl_));
;     const int lane = tidl_ & 63, wid = tidl_ >> 6, wr = wid >> 2, wc = wid & 3, fr = lane & 15, fq = lane >> 4;
;     G_EPI_LOOP {
;       size_t o = (size_t)mt * 256 + G_J;
;       int ncol = nt * 256 + G_I;
;       float* dp = p.out + o * 1024 + ncol;
;       f32x4 res = *(const f32x4*)dp;
;       *(f32x4*)dp = res + acc[ai][bj][m][n];
;       if (n == 1) asm volatile("" ::: "memory");
;     }
.LBB0_381:
	s_or_b64 exec, exec, s[30:31]
	v_mov_b32_e32 v128, v140
	s_waitcnt vmcnt(0)
	s_barrier
	s_lshl_b64 s[30:31], s[2:3], 20
	v_and_b32_e32 v130, 15, v128
	v_lshrrev_b32_e32 v131, 1, v128
	v_and_or_b32 v130, v131, s47, v130
	v_lshl_add_u32 v250, s2, 8, v130
	v_ashrrev_i32_e32 v131, 2, v128
	v_and_b32_e32 v131, 0xffffffc0, v131
	v_lshrrev_b32_e32 v128, 2, v128
	v_lshl_add_u32 v131, s1, 8, v131
	v_and_or_b32 v138, v128, 12, v131
	s_add_u32 s30, s62, s30
	v_ashrrev_i32_e32 v139, 31, v138
	s_addc_u32 s31, s63, s31
	v_lshlrev_b32_e32 v128, 12, v130
	v_lshl_add_u64 v[146:147], s[30:31], 0, v[128:129]
	v_lshlrev_b64 v[148:149], 2, v[138:139]
	v_lshl_add_u64 v[130:131], v[146:147], 0, v[148:149]
	v_lshl_add_u64 v[132:133], v[130:131], 0, s[22:23]
	v_lshl_add_u64 v[134:135], v[130:131], 0, s[24:25]
	v_lshl_add_u64 v[136:137], v[130:131], 0, s[26:27]
	v_lshlrev_b32_e32 v250, 5, v250
	v_add_u32_e32 v250, 0xc764000, v250
	v_add_u32_e32 v251, 0x1000, v250
	v_mov_b32_e32 v248, 0x3727c5ac
	s_add_i32 s0, s0, s71
	s_add_u32 s28, s28, s71
	s_addc_u32 s29, s29, 0
	s_add_i32 s70, s70, s71
	s_cmp_lt_u32 s0, s33
	global_load_dwordx4 v[204:207], v250, s[90:91]
	global_load_dwordx4 v[208:211], v250, s[90:91] offset:16
	global_load_dwordx4 v[212:215], v250, s[90:91] offset:512
	global_load_dwordx4 v[216:219], v250, s[90:91] offset:528
	global_load_dwordx4 v[220:223], v251, s[90:91]
	global_load_dwordx4 v[224:227], v251, s[90:91] offset:16
	global_load_dwordx4 v[228:231], v251, s[90:91] offset:512
	global_load_dwordx4 v[232:235], v251, s[90:91] offset:528
	global_load_dwordx4 v[156:159], v[130:131], off
	global_load_dwordx4 v[160:163], v[132:133], off
	global_load_dwordx4 v[168:171], v[130:131], off offset:64
	global_load_dwordx4 v[172:175], v[132:133], off offset:64
	global_load_dwordx4 v[176:179], v[130:131], off offset:128
	global_load_dwordx4 v[180:183], v[132:133], off offset:128
	global_load_dwordx4 v[184:187], v[130:131], off offset:192
	global_load_dwordx4 v[188:191], v[132:133], off offset:192
	global_load_dwordx4 v[192:195], v[134:135], off
	global_load_dwordx4 v[196:199], v[136:137], off
	global_load_dwordx4 v[200:203], v[134:135], off offset:64
	s_waitcnt vmcnt(11)
	v_add_f32_e32 v204, v204, v205
	v_add_f32_e32 v206, v206, v207
	v_add_f32_e32 v208, v208, v209
	v_add_f32_e32 v210, v210, v211
	v_add_f32_e32 v204, v204, v206
	v_add_f32_e32 v208, v208, v210
	v_add_f32_e32 v204, v204, v208
	v_fmamk_f32 v204, v204, 0x3a800000, v248
	v_rsq_f32_e32 v204, v204
	s_nop 0
	v_mul_f32_e32 v236, v204, v204
	v_add_f32_e32 v212, v212, v213
	v_add_f32_e32 v214, v214, v215
	v_add_f32_e32 v216, v216, v217
	v_add_f32_e32 v218, v218, v219
	v_add_f32_e32 v212, v212, v214
	v_add_f32_e32 v216, v216, v218
	v_add_f32_e32 v212, v212, v216
	v_fmamk_f32 v212, v212, 0x3a800000, v248
	v_rsq_f32_e32 v212, v212
	s_nop 0
	v_mul_f32_e32 v238, v212, v212
	v_add_f32_e32 v220, v220, v221
	v_add_f32_e32 v222, v222, v223
	v_add_f32_e32 v224, v224, v225
	v_add_f32_e32 v226, v226, v227
	v_add_f32_e32 v220, v220, v222
	v_add_f32_e32 v224, v224, v226
	v_add_f32_e32 v220, v220, v224
	v_fmamk_f32 v220, v220, 0x3a800000, v248
	v_rsq_f32_e32 v220, v220
	s_nop 0
	v_mul_f32_e32 v240, v220, v220
	v_add_f32_e32 v228, v228, v229
	v_add_f32_e32 v230, v230, v231
	v_add_f32_e32 v232, v232, v233
	v_add_f32_e32 v234, v234, v235
	v_add_f32_e32 v228, v228, v230
	v_add_f32_e32 v232, v232, v234
	v_add_f32_e32 v228, v228, v232
	v_fmamk_f32 v228, v228, 0x3a800000, v248
	v_rsq_f32_e32 v228, v228
	s_nop 0
	v_mul_f32_e32 v242, v228, v228
	s_waitcnt vmcnt(10)
	v_pk_mul_f32 v[120:121], v[120:121], v[236:237] op_sel_hi:[1,0]
	v_pk_mul_f32 v[122:123], v[122:123], v[236:237] op_sel_hi:[1,0]
	v_pk_add_f32 v[120:121], v[120:121], v[156:157]
	v_pk_add_f32 v[122:123], v[122:123], v[158:159]
	global_store_dwordx4 v[130:131], v[120:123], off
	global_load_dwordx4 v[156:159], v[136:137], off offset:64
	s_waitcnt vmcnt(11)
	v_pk_mul_f32 v[124:125], v[124:125], v[238:239] op_sel_hi:[1,0]
	v_pk_mul_f32 v[126:127], v[126:127], v[238:239] op_sel_hi:[1,0]
	v_pk_add_f32 v[124:125], v[124:125], v[160:161]
	v_pk_add_f32 v[126:127], v[126:127], v[162:163]
	global_store_dwordx4 v[132:133], v[124:127], off
	global_load_dwordx4 v[160:163], v[134:135], off offset:128
	s_waitcnt vmcnt(12)
	v_pk_mul_f32 v[112:113], v[112:113], v[236:237] op_sel_hi:[1,0]
	v_pk_mul_f32 v[114:115], v[114:115], v[236:237] op_sel_hi:[1,0]
	v_pk_add_f32 v[112:113], v[112:113], v[168:169]
	v_pk_add_f32 v[114:115], v[114:115], v[170:171]
	global_store_dwordx4 v[130:131], v[112:115], off offset:64
	global_load_dwordx4 v[168:171], v[136:137], off offset:128
	s_waitcnt vmcnt(13)
	v_pk_mul_f32 v[116:117], v[116:117], v[238:239] op_sel_hi:[1,0]
	v_pk_mul_f32 v[118:119], v[118:119], v[238:239] op_sel_hi:[1,0]
	v_pk_add_f32 v[116:117], v[116:117], v[172:173]
	v_pk_add_f32 v[118:119], v[118:119], v[174:175]
	global_store_dwordx4 v[132:133], v[116:119], off offset:64
	global_load_dwordx4 v[172:175], v[134:135], off offset:192
	s_waitcnt vmcnt(14)
	v_pk_mul_f32 v[104:105], v[104:105], v[236:237] op_sel_hi:[1,0]
	v_pk_mul_f32 v[106:107], v[106:107], v[236:237] op_sel_hi:[1,0]
	v_pk_add_f32 v[104:105], v[104:105], v[176:177]
	v_pk_add_f32 v[106:107], v[106:107], v[178:179]
	global_store_dwordx4 v[130:131], v[104:107], off offset:128
	global_load_dwordx4 v[176:179], v[136:137], off offset:192
	s_waitcnt vmcnt(15)
	v_pk_mul_f32 v[108:109], v[108:109], v[238:239] op_sel_hi:[1,0]
	v_pk_mul_f32 v[110:111], v[110:111], v[238:239] op_sel_hi:[1,0]
	v_pk_add_f32 v[108:109], v[108:109], v[180:181]
	v_pk_add_f32 v[110:111], v[110:111], v[182:183]
	global_store_dwordx4 v[132:133], v[108:111], off offset:128
	global_load_dwordx4 v[180:183], v[130:131], off offset:512
	s_waitcnt vmcnt(16)
; #define G_EPI_LOOP                                      \
;   _Pragma("unroll") for (int ai = 0; ai < 2; ++ai)      \
;   _Pragma("unroll") for (int bj = 0; bj < 2; ++bj)      \
;   _Pragma("unroll") for (int m = 0; m < 4; ++m)         \
;   _Pragma("unroll") for (int n = 0; n < 2; ++n)
; DEVI void phase_down(const Params& p, char* lds) {
;     ...
;     G_EPI_LOOP {
;       size_t o = (size_t)mt * 256 + G_J;
;       int ncol = nt * 256 + G_I;
;       float* dp = p.out + o * 1024 + ncol;
;       f32x4 res = *(const f32x4*)dp;
;       *(f32x4*)dp = res + acc[ai][bj][m][n];
;       if (n == 1) asm volatile("" ::: "memory");
;     }
	v_pk_mul_f32 v[96:97], v[96:97], v[236:237] op_sel_hi:[1,0]
	v_pk_mul_f32 v[98:99], v[98:99], v[236:237] op_sel_hi:[1,0]
	v_pk_add_f32 v[96:97], v[96:97], v[184:185]
	v_pk_add_f32 v[98:99], v[98:99], v[186:187]
	global_store_dwordx4 v[130:131], v[96:99], off offset:192
	global_load_dwordx4 v[184:187], v[132:133], off offset:512
	s_waitcnt vmcnt(17)
	v_pk_mul_f32 v[100:101], v[100:101], v[238:239] op_sel_hi:[1,0]
	v_pk_mul_f32 v[102:103], v[102:103], v[238:239] op_sel_hi:[1,0]
	v_pk_add_f32 v[100:101], v[100:101], v[188:189]
	v_pk_add_f32 v[102:103], v[102:103], v[190:191]
	global_store_dwordx4 v[132:133], v[100:103], off offset:192
	global_load_dwordx4 v[188:191], v[130:131], off offset:576
	s_waitcnt vmcnt(18)
	v_pk_mul_f32 v[88:89], v[88:89], v[240:241] op_sel_hi:[1,0]
	v_pk_mul_f32 v[90:91], v[90:91], v[240:241] op_sel_hi:[1,0]
	v_pk_add_f32 v[88:89], v[88:89], v[192:193]
	v_pk_add_f32 v[90:91], v[90:91], v[194:195]
	global_store_dwordx4 v[134:135], v[88:91], off
	global_load_dwordx4 v[192:195], v[132:133], off offset:576
	s_waitcnt vmcnt(19)
	v_pk_mul_f32 v[92:93], v[92:93], v[242:243] op_sel_hi:[1,0]
	v_pk_mul_f32 v[94:95], v[94:95], v[242:243] op_sel_hi:[1,0]
	v_pk_add_f32 v[92:93], v[92:93], v[196:197]
	v_pk_add_f32 v[94:95], v[94:95], v[198:199]
	global_store_dwordx4 v[136:137], v[92:95], off
	global_load_dwordx4 v[196:199], v[130:131], off offset:640
	s_waitcnt vmcnt(20)
	v_pk_mul_f32 v[80:81], v[80:81], v[240:241] op_sel_hi:[1,0]
	v_pk_mul_f32 v[82:83], v[82:83], v[240:241] op_sel_hi:[1,0]
	v_pk_add_f32 v[80:81], v[80:81], v[200:201]
	v_pk_add_f32 v[82:83], v[82:83], v[202:203]
	global_store_dwordx4 v[134:135], v[80:83], off offset:64
	global_load_dwordx4 v[200:203], v[132:133], off offset:640
	s_waitcnt vmcnt(20)
	v_pk_mul_f32 v[84:85], v[84:85], v[242:243] op_sel_hi:[1,0]
	v_pk_mul_f32 v[86:87], v[86:87], v[242:243] op_sel_hi:[1,0]
	v_pk_add_f32 v[84:85], v[84:85], v[156:157]
	v_pk_add_f32 v[86:87], v[86:87], v[158:159]
	global_store_dwordx4 v[136:137], v[84:87], off offset:64
	global_load_dwordx4 v[156:159], v[130:131], off offset:704
	s_waitcnt vmcnt(20)
	v_pk_mul_f32 v[72:73], v[72:73], v[240:241] op_sel_hi:[1,0]
	v_pk_mul_f32 v[74:75], v[74:75], v[240:241] op_sel_hi:[1,0]
	v_pk_add_f32 v[72:73], v[72:73], v[160:161]
	v_pk_add_f32 v[74:75], v[74:75], v[162:163]
	global_store_dwordx4 v[134:135], v[72:75], off offset:128
	global_load_dwordx4 v[160:163], v[132:133], off offset:704
	s_waitcnt vmcnt(20)
	v_pk_mul_f32 v[76:77], v[76:77], v[242:243] op_sel_hi:[1,0]
	v_pk_mul_f32 v[78:79], v[78:79], v[242:243] op_sel_hi:[1,0]
	v_pk_add_f32 v[76:77], v[76:77], v[168:169]
	v_pk_add_f32 v[78:79], v[78:79], v[170:171]
	global_store_dwordx4 v[136:137], v[76:79], off offset:128
	global_load_dwordx4 v[168:171], v[134:135], off offset:512
	s_waitcnt vmcnt(20)
	v_pk_mul_f32 v[68:69], v[68:69], v[240:241] op_sel_hi:[1,0]
	v_pk_mul_f32 v[70:71], v[70:71], v[240:241] op_sel_hi:[1,0]
	v_pk_add_f32 v[68:69], v[68:69], v[172:173]
	v_pk_add_f32 v[70:71], v[70:71], v[174:175]
	global_store_dwordx4 v[134:135], v[68:71], off offset:192
	global_load_dwordx4 v[172:175], v[136:137], off offset:512
	s_waitcnt vmcnt(20)
	v_pk_mul_f32 v[64:65], v[64:65], v[242:243] op_sel_hi:[1,0]
	v_pk_mul_f32 v[66:67], v[66:67], v[242:243] op_sel_hi:[1,0]
	v_pk_add_f32 v[64:65], v[64:65], v[176:177]
	v_pk_add_f32 v[66:67], v[66:67], v[178:179]
	global_store_dwordx4 v[136:137], v[64:67], off offset:192
	global_load_dwordx4 v[176:179], v[134:135], off offset:576
	s_waitcnt vmcnt(20)
	v_pk_mul_f32 v[60:61], v[60:61], v[236:237] op_sel_hi:[1,0]
	v_pk_mul_f32 v[62:63], v[62:63], v[236:237] op_sel_hi:[1,0]
	v_pk_add_f32 v[60:61], v[60:61], v[180:181]
	v_pk_add_f32 v[62:63], v[62:63], v[182:183]
	global_store_dwordx4 v[130:131], v[60:63], off offset:512
	global_load_dwordx4 v[180:183], v[136:137], off offset:576
	s_waitcnt vmcnt(20)
	v_pk_mul_f32 v[56:57], v[56:57], v[238:239] op_sel_hi:[1,0]
	v_pk_mul_f32 v[58:59], v[58:59], v[238:239] op_sel_hi:[1,0]
	v_pk_add_f32 v[56:57], v[56:57], v[184:185]
	v_pk_add_f32 v[58:59], v[58:59], v[186:187]
	global_store_dwordx4 v[132:133], v[56:59], off offset:512
	global_load_dwordx4 v[184:187], v[134:135], off offset:640
	s_waitcnt vmcnt(20)
; #define G_EPI_LOOP                                      \
;   _Pragma("unroll") for (int ai = 0; ai < 2; ++ai)      \
;   _Pragma("unroll") for (int bj = 0; bj < 2; ++bj)      \
;   _Pragma("unroll") for (int m = 0; m < 4; ++m)         \
;   _Pragma("unroll") for (int n = 0; n < 2; ++n)
; DEVI void phase_down(const Params& p, char* lds) {
;     ...
;     G_EPI_LOOP {
;       size_t o = (size_t)mt * 256 + G_J;
;       int ncol = nt * 256 + G_I;
;       float* dp = p.out + o * 1024 + ncol;
;       f32x4 res = *(const f32x4*)dp;
;       *(f32x4*)dp = res + acc[ai][bj][m][n];
;       if (n == 1) asm volatile("" ::: "memory");
;     }
	v_pk_mul_f32 v[52:53], v[52:53], v[236:237] op_sel_hi:[1,0]
	v_pk_mul_f32 v[54:55], v[54:55], v[236:237] op_sel_hi:[1,0]
	v_pk_add_f32 v[52:53], v[52:53], v[188:189]
	v_pk_add_f32 v[54:55], v[54:55], v[190:191]
	global_store_dwordx4 v[130:131], v[52:55], off offset:576
	global_load_dwordx4 v[188:191], v[136:137], off offset:640
	s_waitcnt vmcnt(20)
	v_pk_mul_f32 v[48:49], v[48:49], v[238:239] op_sel_hi:[1,0]
	v_pk_mul_f32 v[50:51], v[50:51], v[238:239] op_sel_hi:[1,0]
	v_pk_add_f32 v[48:49], v[48:49], v[192:193]
	v_pk_add_f32 v[50:51], v[50:51], v[194:195]
	global_store_dwordx4 v[132:133], v[48:51], off offset:576
	global_load_dwordx4 v[192:195], v[134:135], off offset:704
	s_waitcnt vmcnt(20)
	v_pk_mul_f32 v[44:45], v[44:45], v[236:237] op_sel_hi:[1,0]
	v_pk_mul_f32 v[46:47], v[46:47], v[236:237] op_sel_hi:[1,0]
	v_pk_add_f32 v[44:45], v[44:45], v[196:197]
	v_pk_add_f32 v[46:47], v[46:47], v[198:199]
	global_store_dwordx4 v[130:131], v[44:47], off offset:640
	global_load_dwordx4 v[196:199], v[136:137], off offset:704
	s_waitcnt vmcnt(20)
	v_pk_mul_f32 v[40:41], v[40:41], v[238:239] op_sel_hi:[1,0]
	v_pk_mul_f32 v[42:43], v[42:43], v[238:239] op_sel_hi:[1,0]
	v_pk_add_f32 v[40:41], v[40:41], v[200:201]
	v_pk_add_f32 v[42:43], v[42:43], v[202:203]
	global_store_dwordx4 v[132:133], v[40:43], off offset:640
	s_waitcnt vmcnt(19)
	v_pk_mul_f32 v[36:37], v[36:37], v[236:237] op_sel_hi:[1,0]
	v_pk_mul_f32 v[38:39], v[38:39], v[236:237] op_sel_hi:[1,0]
	v_pk_add_f32 v[36:37], v[36:37], v[156:157]
	v_pk_add_f32 v[38:39], v[38:39], v[158:159]
	global_store_dwordx4 v[130:131], v[36:39], off offset:704
	s_waitcnt vmcnt(18)
	v_pk_mul_f32 v[32:33], v[32:33], v[238:239] op_sel_hi:[1,0]
	v_pk_mul_f32 v[34:35], v[34:35], v[238:239] op_sel_hi:[1,0]
	v_pk_add_f32 v[32:33], v[32:33], v[160:161]
	v_pk_add_f32 v[34:35], v[34:35], v[162:163]
	global_store_dwordx4 v[132:133], v[32:35], off offset:704
	s_waitcnt vmcnt(17)
	v_pk_mul_f32 v[28:29], v[28:29], v[240:241] op_sel_hi:[1,0]
	v_pk_mul_f32 v[30:31], v[30:31], v[240:241] op_sel_hi:[1,0]
	v_pk_add_f32 v[28:29], v[28:29], v[168:169]
	v_pk_add_f32 v[30:31], v[30:31], v[170:171]
	global_store_dwordx4 v[134:135], v[28:31], off offset:512
	s_waitcnt vmcnt(16)
	v_pk_mul_f32 v[24:25], v[24:25], v[242:243] op_sel_hi:[1,0]
	v_pk_mul_f32 v[26:27], v[26:27], v[242:243] op_sel_hi:[1,0]
	v_pk_add_f32 v[24:25], v[24:25], v[172:173]
	v_pk_add_f32 v[26:27], v[26:27], v[174:175]
	global_store_dwordx4 v[136:137], v[24:27], off offset:512
	s_waitcnt vmcnt(15)
	v_pk_mul_f32 v[20:21], v[20:21], v[240:241] op_sel_hi:[1,0]
	v_pk_mul_f32 v[22:23], v[22:23], v[240:241] op_sel_hi:[1,0]
	v_pk_add_f32 v[20:21], v[20:21], v[176:177]
	v_pk_add_f32 v[22:23], v[22:23], v[178:179]
	global_store_dwordx4 v[134:135], v[20:23], off offset:576
	s_waitcnt vmcnt(14)
	v_pk_mul_f32 v[16:17], v[16:17], v[242:243] op_sel_hi:[1,0]
	v_pk_mul_f32 v[18:19], v[18:19], v[242:243] op_sel_hi:[1,0]
	v_pk_add_f32 v[16:17], v[16:17], v[180:181]
	v_pk_add_f32 v[18:19], v[18:19], v[182:183]
	global_store_dwordx4 v[136:137], v[16:19], off offset:576
	s_waitcnt vmcnt(13)
	v_pk_mul_f32 v[12:13], v[12:13], v[240:241] op_sel_hi:[1,0]
	v_pk_mul_f32 v[14:15], v[14:15], v[240:241] op_sel_hi:[1,0]
	v_pk_add_f32 v[12:13], v[12:13], v[184:185]
	v_pk_add_f32 v[14:15], v[14:15], v[186:187]
	global_store_dwordx4 v[134:135], v[12:15], off offset:640
	s_waitcnt vmcnt(12)
	v_pk_mul_f32 v[8:9], v[8:9], v[242:243] op_sel_hi:[1,0]
	v_pk_mul_f32 v[10:11], v[10:11], v[242:243] op_sel_hi:[1,0]
	v_pk_add_f32 v[8:9], v[8:9], v[188:189]
	v_pk_add_f32 v[10:11], v[10:11], v[190:191]
	global_store_dwordx4 v[136:137], v[8:11], off offset:640
	s_waitcnt vmcnt(11)
	v_pk_mul_f32 v[0:1], v[0:1], v[240:241] op_sel_hi:[1,0]
	v_pk_mul_f32 v[2:3], v[2:3], v[240:241] op_sel_hi:[1,0]
	v_pk_add_f32 v[0:1], v[0:1], v[192:193]
	v_pk_add_f32 v[2:3], v[2:3], v[194:195]
	global_store_dwordx4 v[134:135], v[0:3], off offset:704
	s_waitcnt vmcnt(10)
	v_pk_mul_f32 v[4:5], v[4:5], v[242:243] op_sel_hi:[1,0]
	v_pk_mul_f32 v[6:7], v[6:7], v[242:243] op_sel_hi:[1,0]
	v_pk_add_f32 v[4:5], v[4:5], v[196:197]
	v_pk_add_f32 v[6:7], v[6:7], v[198:199]
	global_store_dwordx4 v[136:137], v[4:7], off offset:704
	s_cbranch_scc0 .LBB0_388
